# v95 + the first arriver of each XCC starts an L2 write-back at arrival (not waited), so the last arriver's release write-back has less left to flush
# speedup vs baseline: 1.0032x; 1.0032x over previous
; __device__ __forceinline__ unsigned xb_ld(unsigned* p)              { return __hip_atomic_load(p, __ATOMIC_RELAXED, __HIP_MEMORY_SCOPE_AGENT); }
; __device__ __forceinline__ unsigned xb_add(unsigned* p, unsigned v) { return __hip_atomic_fetch_add(p, v, __ATOMIC_RELAXED, __HIP_MEMORY_SCOPE_AGENT); }
; #define XB_SPIN(cond, bar) do { unsigned _sp = 0; while (cond) { __builtin_amdgcn_s_sleep(1); \
;     if ((++_sp & 255u) == 0u) { if (xb_ld(&(bar)[XB_TMO])) break; if (_sp > XB_SPIN_CAP) { atomicAdd(&(bar)[XB_TMO], 1u); break; } } } } while (0)
; __device__ __forceinline__ void xcd_barrier(const XcdBarrier& b) {
;     asm volatile("s_waitcnt vmcnt(0)" ::: "memory");
;     __syncthreads();
;     if (threadIdx.x == 0) {
;         unsigned* bar = b.bar;
;         __builtin_amdgcn_s_waitcnt(0);
;         unsigned nloc = b.st[0], nx = b.st[1];
;         if (nloc == 0u) { xcd_barrier_complete(bar, b.x, nloc, nx); b.st[0] = nloc; b.st[1] = nx; }
;         const unsigned old = xb_add(&bar[XB_XSUB(b.x)], 1u);
;         const unsigned gen = old / nloc;
;         if (old + 1u == (gen + 1u) * nloc) {
;             __builtin_amdgcn_fence(__ATOMIC_RELEASE, "agent");
;             asm volatile("s_waitcnt vmcnt(0)" ::: "memory");
;             const unsigned og = xb_add(&bar[XB_TOP], 1u);
;             const unsigned tg = og / nx;
;             if (og + 1u == (tg + 1u) * nx) xb_add(&bar[XB_TOPGEN], 1u);
;             else XB_SPIN(xb_ld(&bar[XB_TOPGEN]) == tg, bar);
;             __builtin_amdgcn_fence(__ATOMIC_ACQUIRE, "agent");
;             xb_add(&bar[XB_XGEN(b.x)], 1u);
.Lgb0_census_ok:
	s_max_u32 s11, s11, 1
	s_max_u32 s22, s10, 1
	v_mov_b32_e32 v6, 0x23fc0
	v_mov_b32_e32 v7, s11
	ds_write_b32 v6, v7
	v_mov_b32_e32 v7, s22
	ds_write_b32 v6, v7 offset:4
	s_add_i32 s23, s8, 0x1000
	v_mov_b32_e32 v4, s23
	global_atomic_add v6, v4, v1, s[84:85] offset:1024 sc0
	s_waitcnt vmcnt(0) lgkmcnt(0)
	v_readfirstlane_b32 s9, v6
	s_mov_b32 s23, 0
	s_add_i32 s9, s9, 1
	s_add_i32 s23, s23, 1
	v_mov_b32_e32 v4, 0x3000
	s_mov_b32 s24, 0
	s_cmp_eq_u32 s9, s11
	s_cbranch_scc1 .Lgb0_last
	s_cmp_eq_u32 s9, s23
	s_cbranch_scc0 .Lgb0_poll
	buffer_wbl2 sc1
	s_branch .Lgb0_poll
.Lgb0_last:
	buffer_wbl2 sc1
	s_waitcnt vmcnt(0)
	global_atomic_add v4, v1, s[84:85] offset:1024

; __device__ __forceinline__ unsigned xb_ld(unsigned* p)              { return __hip_atomic_load(p, __ATOMIC_RELAXED, __HIP_MEMORY_SCOPE_AGENT); }
; __device__ __forceinline__ unsigned xb_add(unsigned* p, unsigned v) { return __hip_atomic_fetch_add(p, v, __ATOMIC_RELAXED, __HIP_MEMORY_SCOPE_AGENT); }
; #define XB_SPIN(cond, bar) do { unsigned _sp = 0; while (cond) { __builtin_amdgcn_s_sleep(1); \
;     if ((++_sp & 255u) == 0u) { if (xb_ld(&(bar)[XB_TMO])) break; if (_sp > XB_SPIN_CAP) { atomicAdd(&(bar)[XB_TMO], 1u); break; } } } } while (0)
; __device__ __forceinline__ void xcd_barrier(const XcdBarrier& b) {
;     asm volatile("s_waitcnt vmcnt(0)" ::: "memory");
;     __syncthreads();
;     if (threadIdx.x == 0) {
;         unsigned* bar = b.bar;
;         __builtin_amdgcn_s_waitcnt(0);
;         unsigned nloc = b.st[0], nx = b.st[1];
;         if (nloc == 0u) { xcd_barrier_complete(bar, b.x, nloc, nx); b.st[0] = nloc; b.st[1] = nx; }
;         const unsigned old = xb_add(&bar[XB_XSUB(b.x)], 1u);
;         const unsigned gen = old / nloc;
;         if (old + 1u == (gen + 1u) * nloc) {
;             __builtin_amdgcn_fence(__ATOMIC_RELEASE, "agent");
;             asm volatile("s_waitcnt vmcnt(0)" ::: "memory");
;             const unsigned og = xb_add(&bar[XB_TOP], 1u);
;             const unsigned tg = og / nx;
;             if (og + 1u == (tg + 1u) * nx) xb_add(&bar[XB_TOPGEN], 1u);
;             else XB_SPIN(xb_ld(&bar[XB_TOPGEN]) == tg, bar);
;             __builtin_amdgcn_fence(__ATOMIC_ACQUIRE, "agent");
;             xb_add(&bar[XB_XGEN(b.x)], 1u);
; __global__ void __launch_bounds__(512) fwd_kernel(Params p_unused) {
;     ...
;     xcd_barrier(xb);
.LBB0_178:
	s_waitcnt vmcnt(0)
	s_waitcnt vmcnt(0)
	s_barrier
	s_mov_b64 s[0:1], exec
	v_readlane_b32 s4, v252, 6
	v_readlane_b32 s5, v252, 7
	s_and_b64 s[4:5], s[0:1], s[4:5]
	s_mov_b64 exec, s[4:5]
	s_cbranch_execz .LBB0_236
	s_waitcnt vmcnt(0) expcnt(0) lgkmcnt(0)
	buffer_inv sc1
	v_mov_b32_e32 v0, 0x23fc0
	ds_read_b32 v2, v0
	ds_read_b32 v3, v0 offset:4
	v_readlane_b32 s3, v252, 5
	s_lshl_b32 s8, s3, 8
	v_mov_b32_e32 v1, 1
	s_add_i32 s23, s8, 0x1000
	v_mov_b32_e32 v4, s23
	global_atomic_add v6, v4, v1, s[84:85] offset:1024 sc0
	s_waitcnt vmcnt(0) lgkmcnt(0)
	v_readfirstlane_b32 s9, v6
	v_readfirstlane_b32 s11, v2
	v_readfirstlane_b32 s22, v3
	s_mul_i32 s23, s11, 1
	s_mul_i32 s11, s11, 2
	s_mul_i32 s22, s22, 2
	s_add_i32 s9, s9, 1
	s_add_i32 s23, s23, 1
	v_mov_b32_e32 v4, 0x3000
	s_mov_b32 s24, 0
	s_cmp_eq_u32 s9, s11
	s_cbranch_scc1 .Lgb1_last
	s_cmp_eq_u32 s9, s23
	s_cbranch_scc0 .Lgb1_poll
	buffer_wbl2 sc1
	s_branch .Lgb1_poll

; __device__ __forceinline__ unsigned xb_ld(unsigned* p)              { return __hip_atomic_load(p, __ATOMIC_RELAXED, __HIP_MEMORY_SCOPE_AGENT); }
; __device__ __forceinline__ unsigned xb_add(unsigned* p, unsigned v) { return __hip_atomic_fetch_add(p, v, __ATOMIC_RELAXED, __HIP_MEMORY_SCOPE_AGENT); }
; #define XB_SPIN(cond, bar) do { unsigned _sp = 0; while (cond) { __builtin_amdgcn_s_sleep(1); \
;     if ((++_sp & 255u) == 0u) { if (xb_ld(&(bar)[XB_TMO])) break; if (_sp > XB_SPIN_CAP) { atomicAdd(&(bar)[XB_TMO], 1u); break; } } } } while (0)
; __device__ __forceinline__ void xcd_barrier(const XcdBarrier& b) {
;     asm volatile("s_waitcnt vmcnt(0)" ::: "memory");
;     __syncthreads();
;     if (threadIdx.x == 0) {
;         unsigned* bar = b.bar;
;         __builtin_amdgcn_s_waitcnt(0);
;         unsigned nloc = b.st[0], nx = b.st[1];
;         if (nloc == 0u) { xcd_barrier_complete(bar, b.x, nloc, nx); b.st[0] = nloc; b.st[1] = nx; }
;         const unsigned old = xb_add(&bar[XB_XSUB(b.x)], 1u);
;         const unsigned gen = old / nloc;
;         if (old + 1u == (gen + 1u) * nloc) {
;             __builtin_amdgcn_fence(__ATOMIC_RELEASE, "agent");
;             asm volatile("s_waitcnt vmcnt(0)" ::: "memory");
;             const unsigned og = xb_add(&bar[XB_TOP], 1u);
;             const unsigned tg = og / nx;
;             if (og + 1u == (tg + 1u) * nx) xb_add(&bar[XB_TOPGEN], 1u);
;             else XB_SPIN(xb_ld(&bar[XB_TOPGEN]) == tg, bar);
;             __builtin_amdgcn_fence(__ATOMIC_ACQUIRE, "agent");
;             xb_add(&bar[XB_XGEN(b.x)], 1u);
; __global__ void __launch_bounds__(512) fwd_kernel(Params p_unused) {
;     ...
;     xcd_barrier(xb);
.LBB0_279:
	s_waitcnt vmcnt(0)
	s_barrier
	s_mov_b64 s[0:1], exec
	v_readlane_b32 s4, v252, 6
	v_readlane_b32 s5, v252, 7
	s_and_b64 s[4:5], s[0:1], s[4:5]
	s_mov_b64 exec, s[4:5]
	s_cbranch_execz .LBB0_331
	s_waitcnt vmcnt(0) expcnt(0) lgkmcnt(0)
	buffer_inv sc1
	v_mov_b32_e32 v0, 0x23fc0
	ds_read_b32 v2, v0
	ds_read_b32 v3, v0 offset:4
	v_readlane_b32 s3, v252, 5
	s_lshl_b32 s8, s3, 8
	v_mov_b32_e32 v1, 1
	s_add_i32 s23, s8, 0x1000
	v_mov_b32_e32 v4, s23
	global_atomic_add v6, v4, v1, s[84:85] offset:1024 sc0
	s_waitcnt vmcnt(0) lgkmcnt(0)
	v_readfirstlane_b32 s9, v6
	v_readfirstlane_b32 s11, v2
	v_readfirstlane_b32 s22, v3
	s_mul_i32 s23, s11, 2
	s_mul_i32 s11, s11, 3
	s_mul_i32 s22, s22, 3
	s_add_i32 s9, s9, 1
	s_add_i32 s23, s23, 1
	v_mov_b32_e32 v4, 0x3000
	s_mov_b32 s24, 0
	s_cmp_eq_u32 s9, s11
	s_cbranch_scc1 .Lgb2_last
	s_cmp_eq_u32 s9, s23
	s_cbranch_scc0 .Lgb2_poll
	buffer_wbl2 sc1
	s_branch .Lgb2_poll

; __device__ __forceinline__ unsigned xb_ld(unsigned* p)              { return __hip_atomic_load(p, __ATOMIC_RELAXED, __HIP_MEMORY_SCOPE_AGENT); }
; __device__ __forceinline__ unsigned xb_add(unsigned* p, unsigned v) { return __hip_atomic_fetch_add(p, v, __ATOMIC_RELAXED, __HIP_MEMORY_SCOPE_AGENT); }
; #define XB_SPIN(cond, bar) do { unsigned _sp = 0; while (cond) { __builtin_amdgcn_s_sleep(1); \
;     if ((++_sp & 255u) == 0u) { if (xb_ld(&(bar)[XB_TMO])) break; if (_sp > XB_SPIN_CAP) { atomicAdd(&(bar)[XB_TMO], 1u); break; } } } } while (0)
; __device__ __forceinline__ void xcd_barrier(const XcdBarrier& b) {
;     asm volatile("s_waitcnt vmcnt(0)" ::: "memory");
;     __syncthreads();
;     if (threadIdx.x == 0) {
;         unsigned* bar = b.bar;
;         __builtin_amdgcn_s_waitcnt(0);
;         unsigned nloc = b.st[0], nx = b.st[1];
;         if (nloc == 0u) { xcd_barrier_complete(bar, b.x, nloc, nx); b.st[0] = nloc; b.st[1] = nx; }
;         const unsigned old = xb_add(&bar[XB_XSUB(b.x)], 1u);
;         const unsigned gen = old / nloc;
;         if (old + 1u == (gen + 1u) * nloc) {
;             __builtin_amdgcn_fence(__ATOMIC_RELEASE, "agent");
;             asm volatile("s_waitcnt vmcnt(0)" ::: "memory");
;             const unsigned og = xb_add(&bar[XB_TOP], 1u);
;             const unsigned tg = og / nx;
;             if (og + 1u == (tg + 1u) * nx) xb_add(&bar[XB_TOPGEN], 1u);
;             else XB_SPIN(xb_ld(&bar[XB_TOPGEN]) == tg, bar);
;             __builtin_amdgcn_fence(__ATOMIC_ACQUIRE, "agent");
;             xb_add(&bar[XB_XGEN(b.x)], 1u);
; __global__ void __launch_bounds__(512) fwd_kernel(Params p_unused) {
;     ...
;     xcd_barrier(xb);
.LBB0_413:
	s_waitcnt vmcnt(0)
	s_barrier
	s_mov_b64 s[0:1], exec
	v_readlane_b32 s4, v252, 6
	v_readlane_b32 s5, v252, 7
	s_and_b64 s[4:5], s[0:1], s[4:5]
	s_mov_b64 exec, s[4:5]
	s_cbranch_execz .LBB0_465
	s_waitcnt vmcnt(0) expcnt(0) lgkmcnt(0)
	buffer_inv sc1
	v_mov_b32_e32 v0, 0x23fc0
	ds_read_b32 v2, v0
	ds_read_b32 v3, v0 offset:4
	v_readlane_b32 s3, v252, 5
	s_lshl_b32 s8, s3, 8
	v_mov_b32_e32 v1, 1
	s_add_i32 s23, s8, 0x1000
	v_mov_b32_e32 v4, s23
	global_atomic_add v6, v4, v1, s[84:85] offset:1024 sc0
	s_waitcnt vmcnt(0) lgkmcnt(0)
	v_readfirstlane_b32 s9, v6
	v_readfirstlane_b32 s11, v2
	v_readfirstlane_b32 s22, v3
	s_mul_i32 s23, s11, 3
	s_mul_i32 s11, s11, 4
	s_mul_i32 s22, s22, 4
	s_add_i32 s9, s9, 1
	s_add_i32 s23, s23, 1
	v_mov_b32_e32 v4, 0x3000
	s_mov_b32 s24, 0
	s_cmp_eq_u32 s9, s11
	s_cbranch_scc1 .Lgb3_last
	s_cmp_eq_u32 s9, s23
	s_cbranch_scc0 .Lgb3_poll
	buffer_wbl2 sc1
	s_branch .Lgb3_poll

; __device__ __forceinline__ unsigned xb_ld(unsigned* p)              { return __hip_atomic_load(p, __ATOMIC_RELAXED, __HIP_MEMORY_SCOPE_AGENT); }
; __device__ __forceinline__ unsigned xb_add(unsigned* p, unsigned v) { return __hip_atomic_fetch_add(p, v, __ATOMIC_RELAXED, __HIP_MEMORY_SCOPE_AGENT); }
; #define XB_SPIN(cond, bar) do { unsigned _sp = 0; while (cond) { __builtin_amdgcn_s_sleep(1); \
;     if ((++_sp & 255u) == 0u) { if (xb_ld(&(bar)[XB_TMO])) break; if (_sp > XB_SPIN_CAP) { atomicAdd(&(bar)[XB_TMO], 1u); break; } } } } while (0)
; __device__ __forceinline__ void xcd_barrier(const XcdBarrier& b) {
;     asm volatile("s_waitcnt vmcnt(0)" ::: "memory");
;     __syncthreads();
;     if (threadIdx.x == 0) {
;         unsigned* bar = b.bar;
;         __builtin_amdgcn_s_waitcnt(0);
;         unsigned nloc = b.st[0], nx = b.st[1];
;         if (nloc == 0u) { xcd_barrier_complete(bar, b.x, nloc, nx); b.st[0] = nloc; b.st[1] = nx; }
;         const unsigned old = xb_add(&bar[XB_XSUB(b.x)], 1u);
;         const unsigned gen = old / nloc;
;         if (old + 1u == (gen + 1u) * nloc) {
;             __builtin_amdgcn_fence(__ATOMIC_RELEASE, "agent");
;             asm volatile("s_waitcnt vmcnt(0)" ::: "memory");
;             const unsigned og = xb_add(&bar[XB_TOP], 1u);
;             const unsigned tg = og / nx;
;             if (og + 1u == (tg + 1u) * nx) xb_add(&bar[XB_TOPGEN], 1u);
;             else XB_SPIN(xb_ld(&bar[XB_TOPGEN]) == tg, bar);
;             __builtin_amdgcn_fence(__ATOMIC_ACQUIRE, "agent");
;             xb_add(&bar[XB_XGEN(b.x)], 1u);
; __global__ void __launch_bounds__(512) fwd_kernel(Params p_unused) {
;     ...
;     xcd_barrier(xb);
.LBB0_470:
	s_or_b64 exec, exec, s[0:1]
	s_waitcnt vmcnt(0)
	s_barrier
	s_mov_b64 s[0:1], exec
	v_readlane_b32 s4, v252, 6
	v_readlane_b32 s5, v252, 7
	s_and_b64 s[4:5], s[0:1], s[4:5]
	s_mov_b64 exec, s[4:5]
	s_cbranch_execz .LBB0_522
	s_waitcnt vmcnt(0) expcnt(0) lgkmcnt(0)
	buffer_inv sc1
	v_mov_b32_e32 v0, 0x23fc0
	ds_read_b32 v2, v0
	ds_read_b32 v3, v0 offset:4
	v_readlane_b32 s3, v252, 5
	s_lshl_b32 s8, s3, 8
	v_mov_b32_e32 v1, 1
	s_add_i32 s23, s8, 0x1000
	v_mov_b32_e32 v4, s23
	global_atomic_add v6, v4, v1, s[84:85] offset:1024 sc0
	s_waitcnt vmcnt(0) lgkmcnt(0)
	v_readfirstlane_b32 s9, v6
	v_readfirstlane_b32 s11, v2
	v_readfirstlane_b32 s22, v3
	s_mul_i32 s23, s11, 4
	s_mul_i32 s11, s11, 5
	s_mul_i32 s22, s22, 5
	s_add_i32 s9, s9, 1
	s_add_i32 s23, s23, 1
	v_mov_b32_e32 v4, 0x3000
	s_mov_b32 s24, 0
	s_cmp_eq_u32 s9, s11
	s_cbranch_scc1 .Lgb4_last
	s_cmp_eq_u32 s9, s23
	s_cbranch_scc0 .Lgb4_poll
	buffer_wbl2 sc1
	s_branch .Lgb4_poll

; __device__ __forceinline__ unsigned xb_ld(unsigned* p)              { return __hip_atomic_load(p, __ATOMIC_RELAXED, __HIP_MEMORY_SCOPE_AGENT); }
; __device__ __forceinline__ unsigned xb_add(unsigned* p, unsigned v) { return __hip_atomic_fetch_add(p, v, __ATOMIC_RELAXED, __HIP_MEMORY_SCOPE_AGENT); }
; #define XB_SPIN(cond, bar) do { unsigned _sp = 0; while (cond) { __builtin_amdgcn_s_sleep(1); \
;     if ((++_sp & 255u) == 0u) { if (xb_ld(&(bar)[XB_TMO])) break; if (_sp > XB_SPIN_CAP) { atomicAdd(&(bar)[XB_TMO], 1u); break; } } } } while (0)
; __device__ __forceinline__ void xcd_barrier(const XcdBarrier& b) {
;     asm volatile("s_waitcnt vmcnt(0)" ::: "memory");
;     __syncthreads();
;     if (threadIdx.x == 0) {
;         unsigned* bar = b.bar;
;         __builtin_amdgcn_s_waitcnt(0);
;         unsigned nloc = b.st[0], nx = b.st[1];
;         if (nloc == 0u) { xcd_barrier_complete(bar, b.x, nloc, nx); b.st[0] = nloc; b.st[1] = nx; }
;         const unsigned old = xb_add(&bar[XB_XSUB(b.x)], 1u);
;         const unsigned gen = old / nloc;
;         if (old + 1u == (gen + 1u) * nloc) {
;             __builtin_amdgcn_fence(__ATOMIC_RELEASE, "agent");
;             asm volatile("s_waitcnt vmcnt(0)" ::: "memory");
;             const unsigned og = xb_add(&bar[XB_TOP], 1u);
;             const unsigned tg = og / nx;
;             if (og + 1u == (tg + 1u) * nx) xb_add(&bar[XB_TOPGEN], 1u);
;             else XB_SPIN(xb_ld(&bar[XB_TOPGEN]) == tg, bar);
;             __builtin_amdgcn_fence(__ATOMIC_ACQUIRE, "agent");
;             xb_add(&bar[XB_XGEN(b.x)], 1u);
; __global__ void __launch_bounds__(512) fwd_kernel(Params p_unused) {
;     ...
;     xcd_barrier(xb);
.LBB0_549:
	s_waitcnt vmcnt(0)
	s_barrier
	s_mov_b64 s[0:1], exec
	v_readlane_b32 s4, v252, 6
	v_readlane_b32 s5, v252, 7
	v_readlane_b32 s66, v252, 10
	s_and_b64 s[4:5], s[0:1], s[4:5]
	v_readlane_b32 s67, v252, 11
	s_mov_b64 exec, s[4:5]
	s_cbranch_execz .LBB0_601
	s_waitcnt vmcnt(0) expcnt(0) lgkmcnt(0)
	buffer_inv sc1
	v_mov_b32_e32 v0, 0x23fc0
	ds_read_b32 v2, v0
	ds_read_b32 v3, v0 offset:4
	v_readlane_b32 s3, v252, 5
	s_lshl_b32 s8, s3, 8
	v_mov_b32_e32 v1, 1
	s_add_i32 s23, s8, 0x1000
	v_mov_b32_e32 v4, s23
	global_atomic_add v6, v4, v1, s[84:85] offset:1024 sc0
	s_waitcnt vmcnt(0) lgkmcnt(0)
	v_readfirstlane_b32 s9, v6
	v_readfirstlane_b32 s11, v2
	v_readfirstlane_b32 s22, v3
	s_mul_i32 s23, s11, 5
	s_mul_i32 s11, s11, 6
	s_mul_i32 s22, s22, 6
	s_add_i32 s9, s9, 1
	s_add_i32 s23, s23, 1
	v_mov_b32_e32 v4, 0x3000
	s_mov_b32 s24, 0
	s_cmp_eq_u32 s9, s11
	s_cbranch_scc1 .Lgb5_last
	s_cmp_eq_u32 s9, s23
	s_cbranch_scc0 .Lgb5_poll
	buffer_wbl2 sc1
	s_branch .Lgb5_poll

; __device__ __forceinline__ unsigned xb_ld(unsigned* p)              { return __hip_atomic_load(p, __ATOMIC_RELAXED, __HIP_MEMORY_SCOPE_AGENT); }
; __device__ __forceinline__ unsigned xb_add(unsigned* p, unsigned v) { return __hip_atomic_fetch_add(p, v, __ATOMIC_RELAXED, __HIP_MEMORY_SCOPE_AGENT); }
; #define XB_SPIN(cond, bar) do { unsigned _sp = 0; while (cond) { __builtin_amdgcn_s_sleep(1); \
;     if ((++_sp & 255u) == 0u) { if (xb_ld(&(bar)[XB_TMO])) break; if (_sp > XB_SPIN_CAP) { atomicAdd(&(bar)[XB_TMO], 1u); break; } } } } while (0)
; __device__ __forceinline__ void xcd_barrier(const XcdBarrier& b) {
;     asm volatile("s_waitcnt vmcnt(0)" ::: "memory");
;     __syncthreads();
;     if (threadIdx.x == 0) {
;         unsigned* bar = b.bar;
;         __builtin_amdgcn_s_waitcnt(0);
;         unsigned nloc = b.st[0], nx = b.st[1];
;         if (nloc == 0u) { xcd_barrier_complete(bar, b.x, nloc, nx); b.st[0] = nloc; b.st[1] = nx; }
;         const unsigned old = xb_add(&bar[XB_XSUB(b.x)], 1u);
;         const unsigned gen = old / nloc;
;         if (old + 1u == (gen + 1u) * nloc) {
;             __builtin_amdgcn_fence(__ATOMIC_RELEASE, "agent");
;             asm volatile("s_waitcnt vmcnt(0)" ::: "memory");
;             const unsigned og = xb_add(&bar[XB_TOP], 1u);
;             const unsigned tg = og / nx;
;             if (og + 1u == (tg + 1u) * nx) xb_add(&bar[XB_TOPGEN], 1u);
;             else XB_SPIN(xb_ld(&bar[XB_TOPGEN]) == tg, bar);
;             __builtin_amdgcn_fence(__ATOMIC_ACQUIRE, "agent");
;             xb_add(&bar[XB_XGEN(b.x)], 1u);
; __global__ void __launch_bounds__(512) fwd_kernel(Params p_unused) {
;     ...
;     xcd_barrier(xb);
.LBB0_608:
	s_or_b64 exec, exec, s[0:1]
	s_waitcnt vmcnt(0)
	s_barrier
	s_mov_b64 s[0:1], exec
	v_readlane_b32 s4, v252, 6
	v_readlane_b32 s5, v252, 7
	s_and_b64 s[4:5], s[0:1], s[4:5]
	s_mov_b64 exec, s[4:5]
	s_cbranch_execz .LBB0_660
	s_waitcnt vmcnt(0) expcnt(0) lgkmcnt(0)
	buffer_inv sc1
	v_mov_b32_e32 v0, 0x23fc0
	ds_read_b32 v2, v0
	ds_read_b32 v3, v0 offset:4
	v_readlane_b32 s3, v252, 5
	s_lshl_b32 s8, s3, 8
	v_mov_b32_e32 v1, 1
	s_add_i32 s23, s8, 0x1000
	v_mov_b32_e32 v4, s23
	global_atomic_add v6, v4, v1, s[84:85] offset:1024 sc0
	s_waitcnt vmcnt(0) lgkmcnt(0)
	v_readfirstlane_b32 s9, v6
	v_readfirstlane_b32 s11, v2
	v_readfirstlane_b32 s22, v3
	s_mul_i32 s23, s11, 6
	s_mul_i32 s11, s11, 7
	s_mul_i32 s22, s22, 7
	s_add_i32 s9, s9, 1
	s_add_i32 s23, s23, 1
	v_mov_b32_e32 v4, 0x3000
	s_mov_b32 s24, 0
	s_cmp_eq_u32 s9, s11
	s_cbranch_scc1 .Lgb6_last
	s_cmp_eq_u32 s9, s23
	s_cbranch_scc0 .Lgb6_poll
	buffer_wbl2 sc1
	s_branch .Lgb6_poll

; __device__ __forceinline__ unsigned xb_ld(unsigned* p)              { return __hip_atomic_load(p, __ATOMIC_RELAXED, __HIP_MEMORY_SCOPE_AGENT); }
; __device__ __forceinline__ unsigned xb_add(unsigned* p, unsigned v) { return __hip_atomic_fetch_add(p, v, __ATOMIC_RELAXED, __HIP_MEMORY_SCOPE_AGENT); }
; #define XB_SPIN(cond, bar) do { unsigned _sp = 0; while (cond) { __builtin_amdgcn_s_sleep(1); \
;     if ((++_sp & 255u) == 0u) { if (xb_ld(&(bar)[XB_TMO])) break; if (_sp > XB_SPIN_CAP) { atomicAdd(&(bar)[XB_TMO], 1u); break; } } } } while (0)
; __device__ __forceinline__ void xcd_barrier(const XcdBarrier& b) {
;     asm volatile("s_waitcnt vmcnt(0)" ::: "memory");
;     __syncthreads();
;     if (threadIdx.x == 0) {
;         unsigned* bar = b.bar;
;         __builtin_amdgcn_s_waitcnt(0);
;         unsigned nloc = b.st[0], nx = b.st[1];
;         if (nloc == 0u) { xcd_barrier_complete(bar, b.x, nloc, nx); b.st[0] = nloc; b.st[1] = nx; }
;         const unsigned old = xb_add(&bar[XB_XSUB(b.x)], 1u);
;         const unsigned gen = old / nloc;
;         if (old + 1u == (gen + 1u) * nloc) {
;             __builtin_amdgcn_fence(__ATOMIC_RELEASE, "agent");
;             asm volatile("s_waitcnt vmcnt(0)" ::: "memory");
;             const unsigned og = xb_add(&bar[XB_TOP], 1u);
;             const unsigned tg = og / nx;
;             if (og + 1u == (tg + 1u) * nx) xb_add(&bar[XB_TOPGEN], 1u);
;             else XB_SPIN(xb_ld(&bar[XB_TOPGEN]) == tg, bar);
;             __builtin_amdgcn_fence(__ATOMIC_ACQUIRE, "agent");
;             xb_add(&bar[XB_XGEN(b.x)], 1u);
; __global__ void __launch_bounds__(512) fwd_kernel(Params p_unused) {
;     ...
;         xcd_barrier(xb);
.LBB0_1087:
	s_waitcnt vmcnt(0)
	s_mov_b64 s[0:1], 0x4000000
	s_barrier
	s_mov_b64 s[4:5], exec
	v_readlane_b32 s6, v252, 6
	v_readlane_b32 s7, v252, 7
	s_and_b64 s[6:7], s[4:5], s[6:7]
	s_mov_b64 exec, s[6:7]
	s_cbranch_execz .LBB0_1139
	s_waitcnt vmcnt(0) expcnt(0) lgkmcnt(0)
	buffer_inv sc1
	v_mov_b32_e32 v0, 0x23fc0
	ds_read_b32 v2, v0
	ds_read_b32 v3, v0 offset:4
	v_readlane_b32 s3, v252, 5
	s_lshl_b32 s8, s3, 8
	v_mov_b32_e32 v1, 1
	s_add_i32 s23, s8, 0x1000
	v_mov_b32_e32 v4, s23
	global_atomic_add v6, v4, v1, s[84:85] offset:1024 sc0
	s_waitcnt vmcnt(0) lgkmcnt(0)
	v_readfirstlane_b32 s9, v6
	v_readfirstlane_b32 s11, v2
	v_readfirstlane_b32 s22, v3
	s_mul_i32 s23, s11, 7
	s_mul_i32 s11, s11, 8
	s_mul_i32 s22, s22, 8
	s_add_i32 s9, s9, 1
	s_add_i32 s23, s23, 1
	v_mov_b32_e32 v4, 0x3000
	s_mov_b32 s24, 0
	s_cmp_eq_u32 s9, s11
	s_cbranch_scc1 .Lgb7_last
	s_cmp_eq_u32 s9, s23
	s_cbranch_scc0 .Lgb7_poll
	buffer_wbl2 sc1
	s_branch .Lgb7_poll

; __device__ __forceinline__ unsigned xb_ld(unsigned* p)              { return __hip_atomic_load(p, __ATOMIC_RELAXED, __HIP_MEMORY_SCOPE_AGENT); }
; __device__ __forceinline__ unsigned xb_add(unsigned* p, unsigned v) { return __hip_atomic_fetch_add(p, v, __ATOMIC_RELAXED, __HIP_MEMORY_SCOPE_AGENT); }
; #define XB_SPIN(cond, bar) do { unsigned _sp = 0; while (cond) { __builtin_amdgcn_s_sleep(1); \
;     if ((++_sp & 255u) == 0u) { if (xb_ld(&(bar)[XB_TMO])) break; if (_sp > XB_SPIN_CAP) { atomicAdd(&(bar)[XB_TMO], 1u); break; } } } } while (0)
; __device__ __forceinline__ void xcd_barrier(const XcdBarrier& b) {
;     asm volatile("s_waitcnt vmcnt(0)" ::: "memory");
;     __syncthreads();
;     if (threadIdx.x == 0) {
;         unsigned* bar = b.bar;
;         __builtin_amdgcn_s_waitcnt(0);
;         unsigned nloc = b.st[0], nx = b.st[1];
;         if (nloc == 0u) { xcd_barrier_complete(bar, b.x, nloc, nx); b.st[0] = nloc; b.st[1] = nx; }
;         const unsigned old = xb_add(&bar[XB_XSUB(b.x)], 1u);
;         const unsigned gen = old / nloc;
;         if (old + 1u == (gen + 1u) * nloc) {
;             __builtin_amdgcn_fence(__ATOMIC_RELEASE, "agent");
;             asm volatile("s_waitcnt vmcnt(0)" ::: "memory");
;             const unsigned og = xb_add(&bar[XB_TOP], 1u);
;             const unsigned tg = og / nx;
;             if (og + 1u == (tg + 1u) * nx) xb_add(&bar[XB_TOPGEN], 1u);
;             else XB_SPIN(xb_ld(&bar[XB_TOPGEN]) == tg, bar);
;             __builtin_amdgcn_fence(__ATOMIC_ACQUIRE, "agent");
;             xb_add(&bar[XB_XGEN(b.x)], 1u);
; __global__ void __launch_bounds__(512) fwd_kernel(Params p_unused) {
;     ...
;         xcd_barrier(xb);
.LBB0_1174:
	s_waitcnt vmcnt(0)
	s_waitcnt vmcnt(0)
	s_barrier
	s_mov_b64 s[0:1], exec
	v_readlane_b32 s4, v252, 6
	v_readlane_b32 s5, v252, 7
	s_and_b64 s[4:5], s[0:1], s[4:5]
	s_mov_b64 exec, s[4:5]
	s_cbranch_execz .LBB0_1226
	s_waitcnt vmcnt(0) expcnt(0) lgkmcnt(0)
	buffer_inv sc1
	v_mov_b32_e32 v0, 0x23fc0
	ds_read_b32 v2, v0
	ds_read_b32 v3, v0 offset:4
	v_readlane_b32 s3, v252, 5
	s_lshl_b32 s8, s3, 8
	v_mov_b32_e32 v1, 1
	s_add_i32 s23, s8, 0x1000
	v_mov_b32_e32 v4, s23
	global_atomic_add v6, v4, v1, s[84:85] offset:1024 sc0
	s_waitcnt vmcnt(0) lgkmcnt(0)
	v_readfirstlane_b32 s9, v6
	v_readfirstlane_b32 s11, v2
	v_readfirstlane_b32 s22, v3
	s_mul_i32 s23, s11, 8
	s_mul_i32 s11, s11, 9
	s_mul_i32 s22, s22, 9
	s_add_i32 s9, s9, 1
	s_add_i32 s23, s23, 1
	v_mov_b32_e32 v4, 0x3000
	s_mov_b32 s24, 0
	s_cmp_eq_u32 s9, s11
	s_cbranch_scc1 .Lgb8_last
	s_cmp_eq_u32 s9, s23
	s_cbranch_scc0 .Lgb8_poll
	buffer_wbl2 sc1
	s_branch .Lgb8_poll
